# cmp2 phase: LDS row stride of the staged hidden rows 512 -> 528 bytes so the 16 rows read by one f32-MFMA A operand fall in 16 different banks (was a 16-way bank conflict)
# speedup vs baseline: 1.0135x; 1.0061x over previous
.LBB0_30:
	s_xor_b64 s[0:1], s[88:89], -1
	v_writelane_b32 v254, s0, 1
	v_lshl_or_b32 v162, s3, 6, v215
	s_mov_b64 s[42:43], 0
	v_writelane_b32 v254, s1, 2
	s_xor_b64 s[0:1], s[4:5], -1
	v_writelane_b32 v254, s0, 3
	s_mov_b64 s[4:5], -1
	s_cmp_lt_i32 s2, 4
	v_writelane_b32 v254, s1, 4
	v_writelane_b32 v254, s80, 5
	s_mov_b64 s[0:1], 0
	s_nop 0
	v_writelane_b32 v254, s81, 6
	v_writelane_b32 v254, s79, 7
	v_writelane_b32 v254, s88, 8
	s_nop 1
	v_writelane_b32 v254, s89, 9
	s_cbranch_scc1 .LBB0_60
	s_cmp_gt_i32 s2, 7
	s_cbranch_scc0 .LBB0_65
	s_cmp_eq_u32 s2, 8
	s_mov_b64 s[0:1], -1
	s_cbranch_scc0 .LBB0_64
	v_and_b32_e32 v4, 63, v215
	v_ashrrev_i32_e32 v0, 6, v162
	v_lshlrev_b32_e32 v160, 1, v4
	v_lshlrev_b32_e32 v5, 10, v0
	v_lshlrev_b32_e32 v50, 1, v0
	v_lshl_add_u64 v[0:1], s[80:81], 0, v[160:161]
	s_mov_b64 s[8:9], 0xc200000
	v_lshl_add_u64 v[6:7], v[0:1], 0, s[8:9]
	v_lshlrev_b32_e32 v0, 4, v215
	s_add_u32 s0, s80, 0xc280000
	v_and_b32_e32 v160, 0x1f0, v0
	s_addc_u32 s1, s81, 0
	v_and_b32_e32 v2, 7, v215
	v_lshlrev_b32_e32 v8, 2, v162
	v_ashrrev_i32_e32 v53, 5, v162
	v_lshl_add_u64 v[0:1], s[80:81], 0, v[160:161]
	s_mov_b64 s[8:9], 0x16600000
	s_cmpk_lt_i32 s79, 0x100
	v_add_u32_e32 v10, 0x800, v8
	v_add_u32_e32 v12, 0x1000, v8
	v_add_u32_e32 v14, 0x1800, v8
	v_add_u32_e32 v16, 0x2000, v8
	v_add_u32_e32 v18, 0x2800, v8
	v_add_u32_e32 v20, 0x3000, v8
	v_add_u32_e32 v22, 0x3800, v8
	v_mul_u32_u24_e32 v3, 0x210, v53
	v_add_u32_e32 v3, 0x10000, v3
	v_lshl_add_u64 v[24:25], v[0:1], 0, s[8:9]
	v_lshlrev_b32_e32 v0, 3, v2
	v_mov_b32_e32 v1, v161
	v_and_b32_e32 v51, 2, v50
	v_cmp_gt_u32_e64 s[4:5], 16, v4
	v_cmp_gt_u32_e64 s[6:7], 8, v4
	v_ashrrev_i32_e32 v9, 31, v8
	v_lshl_add_u32 v52, v162, 4, 0
	v_ashrrev_i32_e32 v11, 31, v10
	v_ashrrev_i32_e32 v13, 31, v12
	v_ashrrev_i32_e32 v15, 31, v14
	v_ashrrev_i32_e32 v17, 31, v16
	v_ashrrev_i32_e32 v19, 31, v18
	v_ashrrev_i32_e32 v21, 31, v20
	v_ashrrev_i32_e32 v23, 31, v22
	v_and_b32_e32 v54, 3, v53
	v_lshl_add_u64 v[26:27], s[80:81], 0, v[0:1]
	v_lshlrev_b32_e32 v55, 2, v4
	s_mov_b64 s[8:9], 0
	s_mov_b64 s[10:11], -1
	s_cselect_b64 s[12:13], -1, 0
	v_add_u32_e32 v56, v3, v160
	s_branch .LBB0_35

.LBB0_45:
	s_or_b64 exec, exec, s[8:9]
	s_waitcnt vmcnt(0)
	ds_write_b128 v52, v[76:79]
	ds_write_b128 v52, v[80:83] offset:8192
	ds_write_b128 v52, v[84:87] offset:16384
	ds_write_b128 v52, v[88:91] offset:24576
	ds_write_b128 v52, v[92:95] offset:32768
	ds_write_b128 v52, v[96:99] offset:40960
	ds_write_b128 v52, v[100:103] offset:49152
	ds_write_b128 v52, v[104:107] offset:57344
	ds_write_b128 v56, v[0:3]
	s_waitcnt lgkmcnt(0)
	s_barrier
	v_and_b32_e32 v0, 15, v4
	v_lshrrev_b32_e32 v1, 4, v4
	v_ashrrev_i32_e32 v2, 6, v162
	v_lshrrev_b32_e32 v3, 2, v2
	v_and_b32_e32 v2, 3, v2
	v_mul_u32_u24_e32 v57, 0x210, v0
	v_lshl_add_u32 v57, v3, 8, v57
	v_lshl_add_u32 v57, v1, 1, v57
	v_add_u32_e32 v57, 0x10000, v57
	v_lshlrev_b32_e32 v58, 15, v3
	v_lshl_add_u32 v58, v1, 8, v58
	v_lshl_add_u32 v58, v2, 6, v58
	v_lshl_add_u32 v58, v0, 2, v58
	v_lshlrev_b32_e32 v59, 12, v3
	v_lshl_add_u32 v59, v1, 10, v59
	v_lshl_add_u32 v59, v2, 6, v59
	v_lshl_add_u32 v59, v0, 2, v59
	v_add_u32_e32 v59, 0x12400, v59
	v_mov_b32_e32 v60, 0
	v_mov_b32_e32 v61, 0
	v_mov_b32_e32 v62, 0
	v_mov_b32_e32 v63, 0
	ds_read_u16 v64, v57 offset:0
	ds_read_u16 v65, v57 offset:8
	ds_read_u16 v66, v57 offset:16
	ds_read_u16 v67, v57 offset:24
	ds_read_u16 v68, v57 offset:32
	ds_read_u16 v69, v57 offset:40
	ds_read_u16 v70, v57 offset:48
	ds_read_u16 v71, v57 offset:56
	ds_read_b32 v72, v58 offset:0
	ds_read_b32 v73, v58 offset:1024
	ds_read_b32 v0, v58 offset:2048
	ds_read_b32 v1, v58 offset:3072
	ds_read_b32 v2, v58 offset:4096
	ds_read_b32 v3, v58 offset:5120
	ds_read_b32 v46, v58 offset:6144
	ds_read_b32 v47, v58 offset:7168
	s_waitcnt lgkmcnt(0)
	v_lshlrev_b32_e32 v64, 16, v64
	v_lshlrev_b32_e32 v65, 16, v65
	v_lshlrev_b32_e32 v66, 16, v66
	v_lshlrev_b32_e32 v67, 16, v67
	v_lshlrev_b32_e32 v68, 16, v68
	v_lshlrev_b32_e32 v69, 16, v69
	v_lshlrev_b32_e32 v70, 16, v70
	v_lshlrev_b32_e32 v71, 16, v71
	v_mfma_f32_16x16x4_f32 v[60:63], v64, v72, v[60:63]
	v_mfma_f32_16x16x4_f32 v[60:63], v65, v73, v[60:63]
	v_mfma_f32_16x16x4_f32 v[60:63], v66, v0, v[60:63]
	v_mfma_f32_16x16x4_f32 v[60:63], v67, v1, v[60:63]
	v_mfma_f32_16x16x4_f32 v[60:63], v68, v2, v[60:63]
	v_mfma_f32_16x16x4_f32 v[60:63], v69, v3, v[60:63]
	v_mfma_f32_16x16x4_f32 v[60:63], v70, v46, v[60:63]
	v_mfma_f32_16x16x4_f32 v[60:63], v71, v47, v[60:63]
	ds_read_u16 v64, v57 offset:64
	ds_read_u16 v65, v57 offset:72
	ds_read_u16 v66, v57 offset:80
	ds_read_u16 v67, v57 offset:88
	ds_read_u16 v68, v57 offset:96
	ds_read_u16 v69, v57 offset:104
	ds_read_u16 v70, v57 offset:112
	ds_read_u16 v71, v57 offset:120
	ds_read_b32 v72, v58 offset:8192
	ds_read_b32 v73, v58 offset:9216
	ds_read_b32 v0, v58 offset:10240
	ds_read_b32 v1, v58 offset:11264
	ds_read_b32 v2, v58 offset:12288
	ds_read_b32 v3, v58 offset:13312
	ds_read_b32 v46, v58 offset:14336
	ds_read_b32 v47, v58 offset:15360
	s_waitcnt lgkmcnt(0)
	v_lshlrev_b32_e32 v64, 16, v64
	v_lshlrev_b32_e32 v65, 16, v65
	v_lshlrev_b32_e32 v66, 16, v66
	v_lshlrev_b32_e32 v67, 16, v67
	v_lshlrev_b32_e32 v68, 16, v68
	v_lshlrev_b32_e32 v69, 16, v69
	v_lshlrev_b32_e32 v70, 16, v70
	v_lshlrev_b32_e32 v71, 16, v71
	v_mfma_f32_16x16x4_f32 v[60:63], v64, v72, v[60:63]
	v_mfma_f32_16x16x4_f32 v[60:63], v65, v73, v[60:63]
	v_mfma_f32_16x16x4_f32 v[60:63], v66, v0, v[60:63]
	v_mfma_f32_16x16x4_f32 v[60:63], v67, v1, v[60:63]
	v_mfma_f32_16x16x4_f32 v[60:63], v68, v2, v[60:63]
	v_mfma_f32_16x16x4_f32 v[60:63], v69, v3, v[60:63]
	v_mfma_f32_16x16x4_f32 v[60:63], v70, v46, v[60:63]
	v_mfma_f32_16x16x4_f32 v[60:63], v71, v47, v[60:63]
	ds_read_u16 v64, v57 offset:128
	ds_read_u16 v65, v57 offset:136
	ds_read_u16 v66, v57 offset:144
	ds_read_u16 v67, v57 offset:152
	ds_read_u16 v68, v57 offset:160
	ds_read_u16 v69, v57 offset:168
	ds_read_u16 v70, v57 offset:176
	ds_read_u16 v71, v57 offset:184
	ds_read_b32 v72, v58 offset:16384
	ds_read_b32 v73, v58 offset:17408
	ds_read_b32 v0, v58 offset:18432
	ds_read_b32 v1, v58 offset:19456
	ds_read_b32 v2, v58 offset:20480
	ds_read_b32 v3, v58 offset:21504
	ds_read_b32 v46, v58 offset:22528
	ds_read_b32 v47, v58 offset:23552
	s_waitcnt lgkmcnt(0)
	v_lshlrev_b32_e32 v64, 16, v64
	v_lshlrev_b32_e32 v65, 16, v65
	v_lshlrev_b32_e32 v66, 16, v66
	v_lshlrev_b32_e32 v67, 16, v67
	v_lshlrev_b32_e32 v68, 16, v68
	v_lshlrev_b32_e32 v69, 16, v69
	v_lshlrev_b32_e32 v70, 16, v70
	v_lshlrev_b32_e32 v71, 16, v71
	v_mfma_f32_16x16x4_f32 v[60:63], v64, v72, v[60:63]
	v_mfma_f32_16x16x4_f32 v[60:63], v65, v73, v[60:63]
	v_mfma_f32_16x16x4_f32 v[60:63], v66, v0, v[60:63]
	v_mfma_f32_16x16x4_f32 v[60:63], v67, v1, v[60:63]
	v_mfma_f32_16x16x4_f32 v[60:63], v68, v2, v[60:63]
	v_mfma_f32_16x16x4_f32 v[60:63], v69, v3, v[60:63]
	v_mfma_f32_16x16x4_f32 v[60:63], v70, v46, v[60:63]
	v_mfma_f32_16x16x4_f32 v[60:63], v71, v47, v[60:63]
	ds_read_u16 v64, v57 offset:192
	ds_read_u16 v65, v57 offset:200
	ds_read_u16 v66, v57 offset:208
	ds_read_u16 v67, v57 offset:216
	ds_read_u16 v68, v57 offset:224
	ds_read_u16 v69, v57 offset:232
	ds_read_u16 v70, v57 offset:240
	ds_read_u16 v71, v57 offset:248
	ds_read_b32 v72, v58 offset:24576
	ds_read_b32 v73, v58 offset:25600
	ds_read_b32 v0, v58 offset:26624
	ds_read_b32 v1, v58 offset:27648
	ds_read_b32 v2, v58 offset:28672
	ds_read_b32 v3, v58 offset:29696
	ds_read_b32 v46, v58 offset:30720
	ds_read_b32 v47, v58 offset:31744
	s_waitcnt lgkmcnt(0)
	v_lshlrev_b32_e32 v64, 16, v64
	v_lshlrev_b32_e32 v65, 16, v65
	v_lshlrev_b32_e32 v66, 16, v66
	v_lshlrev_b32_e32 v67, 16, v67
	v_lshlrev_b32_e32 v68, 16, v68
	v_lshlrev_b32_e32 v69, 16, v69
	v_lshlrev_b32_e32 v70, 16, v70
	v_lshlrev_b32_e32 v71, 16, v71
	v_mfma_f32_16x16x4_f32 v[60:63], v64, v72, v[60:63]
	v_mfma_f32_16x16x4_f32 v[60:63], v65, v73, v[60:63]
	v_mfma_f32_16x16x4_f32 v[60:63], v66, v0, v[60:63]
	v_mfma_f32_16x16x4_f32 v[60:63], v67, v1, v[60:63]
	v_mfma_f32_16x16x4_f32 v[60:63], v68, v2, v[60:63]
	v_mfma_f32_16x16x4_f32 v[60:63], v69, v3, v[60:63]
	v_mfma_f32_16x16x4_f32 v[60:63], v70, v46, v[60:63]
	v_mfma_f32_16x16x4_f32 v[60:63], v71, v47, v[60:63]
	s_nop 7
	s_nop 7
	s_nop 7
	ds_write_b32 v59, v60
	ds_write_b32 v59, v61 offset:256
	ds_write_b32 v59, v62 offset:512
	ds_write_b32 v59, v63 offset:768
	s_waitcnt lgkmcnt(0)
	s_barrier
	v_ashrrev_i32_e32 v0, 6, v162
	v_lshl_add_u32 v0, v0, 9, v55
	v_add_u32_e32 v0, 0x12400, v0
	ds_read_b32 v46, v0
	ds_read_b32 v1, v0 offset:4096
	ds_read_b32 v47, v0 offset:256
	ds_read_b32 v2, v0 offset:4352
	s_waitcnt lgkmcnt(0)
	v_add_f32_e32 v46, v46, v1
	v_add_f32_e32 v47, v47, v2
	v_add_u32_e32 v59, s10, v50
	v_lshrrev_b32_e32 v0, 2, v59
	v_and_b32_e32 v57, 0x7f, v0
	v_cmp_eq_u32_e64 s[10:11], s56, v57
	v_cmp_ne_u32_e64 s[8:9], s56, v57
	s_mov_b64 s[18:19], -1
	s_and_b64 vcc, exec, s[14:15]
	s_cbranch_vccz .LBB0_49
	v_cvt_pk_bf16_f32 v0, v46, s0
	v_cndmask_b32_e64 v60, v0, 0, s[10:11]
	s_mov_b64 s[18:19], 0

.LBB0_276:
	s_add_u32 s3, s20, 0x100
	s_addc_u32 s34, s21, 0
	s_add_u32 s8, s30, 0x80
	v_mov_b64_e32 v[0:1], 0
	v_mov_b64_e32 v[2:3], 0
	v_mov_b64_e32 v[4:5], 0
	v_mov_b64_e32 v[6:7], 0
	v_mov_b64_e32 v[8:9], 0
	v_mov_b64_e32 v[10:11], 0
	v_mov_b64_e32 v[12:13], 0
	v_mov_b64_e32 v[14:15], 0
	v_mov_b64_e32 v[16:17], 0
	v_mov_b64_e32 v[18:19], 0
	v_mov_b64_e32 v[20:21], 0
	v_mov_b64_e32 v[22:23], 0
	v_mov_b64_e32 v[24:25], 0
	v_mov_b64_e32 v[26:27], 0
	v_mov_b64_e32 v[28:29], 0
	v_mov_b64_e32 v[30:31], 0
	v_mov_b64_e32 v[32:33], 0
	v_mov_b64_e32 v[34:35], 0
	v_mov_b64_e32 v[36:37], 0
	v_mov_b64_e32 v[38:39], 0
	v_mov_b64_e32 v[40:41], 0
	v_mov_b64_e32 v[42:43], 0
	v_mov_b64_e32 v[44:45], 0
	v_mov_b64_e32 v[46:47], 0
	v_mov_b64_e32 v[48:49], 0
	v_mov_b64_e32 v[50:51], 0
	v_mov_b64_e32 v[52:53], 0
	v_mov_b64_e32 v[54:55], 0
	v_mov_b64_e32 v[56:57], 0
	v_mov_b64_e32 v[58:59], 0
	v_mov_b64_e32 v[60:61], 0
	v_mov_b64_e32 v[62:63], 0
	v_mov_b64_e32 v[64:65], 0
	v_mov_b64_e32 v[66:67], 0
	v_mov_b64_e32 v[68:69], 0
	v_mov_b64_e32 v[70:71], 0
	v_mov_b64_e32 v[72:73], 0
	v_mov_b64_e32 v[74:75], 0
	v_mov_b64_e32 v[76:77], 0
	v_mov_b64_e32 v[78:79], 0
	v_mov_b64_e32 v[80:81], 0
	v_mov_b64_e32 v[82:83], 0
	v_mov_b64_e32 v[84:85], 0
	v_mov_b64_e32 v[86:87], 0
	v_mov_b64_e32 v[88:89], 0
	v_mov_b64_e32 v[90:91], 0
	v_mov_b64_e32 v[92:93], 0
	v_mov_b64_e32 v[94:95], 0
	v_mov_b64_e32 v[96:97], 0
	v_mov_b64_e32 v[98:99], 0
	v_mov_b64_e32 v[100:101], 0
	v_mov_b64_e32 v[102:103], 0
	v_mov_b64_e32 v[104:105], 0
	v_mov_b64_e32 v[106:107], 0
	v_mov_b64_e32 v[108:109], 0
	v_mov_b64_e32 v[110:111], 0
	v_mov_b64_e32 v[112:113], 0
	v_mov_b64_e32 v[114:115], 0
	v_mov_b64_e32 v[116:117], 0
	v_mov_b64_e32 v[118:119], 0
	v_mov_b64_e32 v[120:121], 0
	v_mov_b64_e32 v[122:123], 0
	v_mov_b64_e32 v[124:125], 0
	v_mov_b64_e32 v[126:127], 0
	s_addc_u32 s9, s31, 0
	s_mov_b32 s20, 0
	s_waitcnt vmcnt(0)
	s_nop 0
	s_nop 0
	s_nop 0
	s_nop 0
	s_nop 0
	s_nop 0
	s_nop 0
	s_nop 0
	s_nop 0
	s_nop 0
	s_nop 0
	s_nop 0
	s_nop 0
	s_nop 0
	s_nop 0
	s_nop 0
	s_nop 0
	s_nop 0
	s_nop 0
	s_nop 0
	s_nop 0
	s_nop 0
	s_nop 0
	s_nop 0
	s_nop 0
	s_nop 0
	s_nop 0
	s_nop 0
	s_nop 0
	s_nop 0
	s_nop 0
	s_nop 0
	s_nop 0
	s_nop 0
	s_nop 0
	s_nop 0
	s_nop 0
	s_nop 0
	s_nop 0
	s_nop 0
	s_nop 0
	s_nop 0
	s_nop 0
	s_nop 0
	s_nop 0
	s_nop 0
	s_nop 0
	s_nop 0
	s_nop 0
	s_nop 0
	s_nop 0
	s_nop 0
	s_nop 0
	s_nop 0
	s_nop 0
	s_nop 0
	s_nop 0
	s_nop 0
	s_nop 0
	s_nop 0
.LBB0_277:
	v_add_u32_e32 v150, s87, v171
	ds_read_b128 v[128:131], v150
	ds_read_b128 v[132:135], v150 offset:1024
	ds_read_b128 v[136:139], v150 offset:2048
	ds_read_b128 v[150:153], v150 offset:3072
	s_add_i32 s35, s20, 2
	s_add_u32 s30, s8, 0x80
	s_addc_u32 s21, s9, 0
	s_cmp_eq_u32 s38, s20
	s_cselect_b32 s20, s76, s30
	s_cselect_b32 s21, s77, s21
	s_cselect_b32 s31, s11, s34
	s_cselect_b32 s30, s10, s3
	v_lshl_add_u64 v[158:159], s[8:9], 0, v[148:149]
	s_add_i32 m0, s26, 0xc000
	ds_read_b128 v[154:157], v173
	ds_read_b128 v[166:169], v173 offset:1024
	ds_read_b128 v[174:177], v173 offset:2048
	ds_read_b128 v[178:181], v173 offset:3072
	ds_read_b128 v[182:185], v173 offset:4096
	ds_read_b128 v[186:189], v173 offset:5120
	ds_read_b128 v[190:193], v173 offset:6144
	ds_read_b128 v[194:197], v173 offset:7168
	global_load_lds_dwordx4 v[158:159], off
	v_lshl_add_u64 v[158:159], s[8:9], 0, v[146:147]
	s_add_i32 m0, s26, 0xe000
	s_nop 0
	global_load_lds_dwordx4 v[158:159], off
	s_waitcnt lgkmcnt(8)
	s_barrier
	s_waitcnt lgkmcnt(0)
	s_waitcnt lgkmcnt(0)
	v_mfma_f32_16x16x32_bf16 v[124:127], v[128:131], v[154:157], v[124:127]
	v_mfma_f32_16x16x32_bf16 v[120:123], v[136:139], v[154:157], v[120:123]
	v_mfma_f32_16x16x32_bf16 v[112:115], v[128:131], v[174:177], v[112:115]
	v_mfma_f32_16x16x32_bf16 v[108:111], v[136:139], v[174:177], v[108:111]
	v_mfma_f32_16x16x32_bf16 v[100:103], v[128:131], v[182:185], v[100:103]
	v_mfma_f32_16x16x32_bf16 v[92:95], v[136:139], v[182:185], v[92:95]
	v_mfma_f32_16x16x32_bf16 v[84:87], v[128:131], v[190:193], v[84:87]
	v_mfma_f32_16x16x32_bf16 v[76:79], v[136:139], v[190:193], v[76:79]
	v_mfma_f32_16x16x32_bf16 v[124:127], v[132:135], v[166:169], v[124:127]
	v_mfma_f32_16x16x32_bf16 v[120:123], v[150:153], v[166:169], v[120:123]
	v_mfma_f32_16x16x32_bf16 v[112:115], v[132:135], v[178:181], v[112:115]
	v_mfma_f32_16x16x32_bf16 v[108:111], v[150:153], v[178:181], v[108:111]
	v_mfma_f32_16x16x32_bf16 v[100:103], v[132:135], v[186:189], v[100:103]
	v_mfma_f32_16x16x32_bf16 v[92:95], v[150:153], v[186:189], v[92:95]
	v_mfma_f32_16x16x32_bf16 v[84:87], v[132:135], v[194:197], v[84:87]
	v_mfma_f32_16x16x32_bf16 v[76:79], v[150:153], v[194:197], v[76:79]
	s_barrier
	s_add_i32 s52, 0, 0x14000
	v_add_u32_e32 v158, s52, v171
	s_add_i32 s78, s87, s23
	ds_read_b128 v[198:201], v158
	ds_read_b128 v[232:235], v158 offset:1024
	ds_read_b128 v[236:239], v158 offset:2048
	ds_read_b128 v[240:243], v158 offset:3072
	v_lshl_add_u64 v[158:159], s[30:31], 0, v[160:161]
	s_mov_b32 m0, s78
	v_lshl_add_u64 v[202:203], s[30:31], 0, v[144:145]
	global_load_lds_dwordx4 v[158:159], off
	s_add_i32 m0, s78, 0x2000
	s_nop 0
	global_load_lds_dwordx4 v[202:203], off
	s_barrier
	s_waitcnt lgkmcnt(0)
	s_waitcnt lgkmcnt(0)
	v_mfma_f32_16x16x32_bf16 v[116:119], v[198:201], v[154:157], v[116:119]
	v_mfma_f32_16x16x32_bf16 v[104:107], v[236:239], v[154:157], v[104:107]
	v_mfma_f32_16x16x32_bf16 v[96:99], v[198:201], v[174:177], v[96:99]
	v_mfma_f32_16x16x32_bf16 v[88:91], v[236:239], v[174:177], v[88:91]
	v_mfma_f32_16x16x32_bf16 v[80:83], v[198:201], v[182:185], v[80:83]
	v_mfma_f32_16x16x32_bf16 v[72:75], v[236:239], v[182:185], v[72:75]
	v_mfma_f32_16x16x32_bf16 v[68:71], v[198:201], v[190:193], v[68:71]
	v_mfma_f32_16x16x32_bf16 v[64:67], v[236:239], v[190:193], v[64:67]
	v_mfma_f32_16x16x32_bf16 v[116:119], v[232:235], v[166:169], v[116:119]
	v_mfma_f32_16x16x32_bf16 v[104:107], v[240:243], v[166:169], v[104:107]
	v_mfma_f32_16x16x32_bf16 v[96:99], v[232:235], v[178:181], v[96:99]
	v_mfma_f32_16x16x32_bf16 v[88:91], v[240:243], v[178:181], v[88:91]
	v_mfma_f32_16x16x32_bf16 v[80:83], v[232:235], v[186:189], v[80:83]
	v_mfma_f32_16x16x32_bf16 v[72:75], v[240:243], v[186:189], v[72:75]
	v_mfma_f32_16x16x32_bf16 v[68:71], v[232:235], v[194:197], v[68:71]
	v_mfma_f32_16x16x32_bf16 v[64:67], v[240:243], v[194:197], v[64:67]
	s_mov_b32 m0, s26
	v_lshl_add_u64 v[206:207], s[20:21], 0, v[140:141]
	s_barrier
	ds_read_b128 v[154:157], v173 offset:16384
	ds_read_b128 v[166:169], v173 offset:17408
	ds_read_b128 v[174:177], v173 offset:18432
	ds_read_b128 v[178:181], v173 offset:19456
	ds_read_b128 v[182:185], v173 offset:20480
	ds_read_b128 v[186:189], v173 offset:21504
	ds_read_b128 v[190:193], v173 offset:22528
	ds_read_b128 v[194:197], v173 offset:23552
	global_load_lds_dwordx4 v[206:207], off
	v_lshl_add_u64 v[210:211], s[20:21], 0, v[142:143]
	s_mov_b32 m0, s16
	s_nop 0
	global_load_lds_dwordx4 v[210:211], off
	s_barrier
	s_waitcnt lgkmcnt(0)
	s_waitcnt lgkmcnt(0)
	v_mfma_f32_16x16x32_bf16 v[60:63], v[128:131], v[154:157], v[60:63]
	v_mfma_f32_16x16x32_bf16 v[56:59], v[136:139], v[154:157], v[56:59]
	v_mfma_f32_16x16x32_bf16 v[52:55], v[128:131], v[174:177], v[52:55]
	v_mfma_f32_16x16x32_bf16 v[44:47], v[136:139], v[174:177], v[44:47]
	v_mfma_f32_16x16x32_bf16 v[36:39], v[128:131], v[182:185], v[36:39]
	v_mfma_f32_16x16x32_bf16 v[28:31], v[136:139], v[182:185], v[28:31]
	v_mfma_f32_16x16x32_bf16 v[20:23], v[128:131], v[190:193], v[20:23]
	v_mfma_f32_16x16x32_bf16 v[12:15], v[136:139], v[190:193], v[12:15]
	v_mfma_f32_16x16x32_bf16 v[60:63], v[132:135], v[166:169], v[60:63]
	v_mfma_f32_16x16x32_bf16 v[56:59], v[150:153], v[166:169], v[56:59]
	v_mfma_f32_16x16x32_bf16 v[52:55], v[132:135], v[178:181], v[52:55]
	v_mfma_f32_16x16x32_bf16 v[44:47], v[150:153], v[178:181], v[44:47]
	v_mfma_f32_16x16x32_bf16 v[36:39], v[132:135], v[186:189], v[36:39]
	v_mfma_f32_16x16x32_bf16 v[28:31], v[150:153], v[186:189], v[28:31]
	v_mfma_f32_16x16x32_bf16 v[20:23], v[132:135], v[194:197], v[20:23]
	v_mfma_f32_16x16x32_bf16 v[12:15], v[150:153], v[194:197], v[12:15]
	s_barrier
	s_add_u32 s30, s30, s64
	s_addc_u32 s31, s31, s65
	s_add_i32 s52, s52, s23
	v_lshl_add_u64 v[244:245], s[30:31], 0, v[160:161]
	s_mov_b32 m0, s52
	v_lshl_add_u64 v[246:247], s[30:31], 0, v[144:145]
	global_load_lds_dwordx4 v[244:245], off
	s_add_i32 m0, s52, 0x2000
	s_nop 0
	global_load_lds_dwordx4 v[246:247], off
	s_waitcnt vmcnt(6)
	s_barrier
	v_mfma_f32_16x16x32_bf16 v[48:51], v[198:201], v[154:157], v[48:51]
	v_mfma_f32_16x16x32_bf16 v[40:43], v[236:239], v[154:157], v[40:43]
	v_mfma_f32_16x16x32_bf16 v[32:35], v[198:201], v[174:177], v[32:35]
	v_mfma_f32_16x16x32_bf16 v[24:27], v[236:239], v[174:177], v[24:27]
	v_mfma_f32_16x16x32_bf16 v[16:19], v[198:201], v[182:185], v[16:19]
	v_mfma_f32_16x16x32_bf16 v[8:11], v[236:239], v[182:185], v[8:11]
	v_mfma_f32_16x16x32_bf16 v[4:7], v[198:201], v[190:193], v[4:7]
	v_mfma_f32_16x16x32_bf16 v[0:3], v[236:239], v[190:193], v[0:3]
	v_mfma_f32_16x16x32_bf16 v[48:51], v[232:235], v[166:169], v[48:51]
	v_mfma_f32_16x16x32_bf16 v[40:43], v[240:243], v[166:169], v[40:43]
	v_mfma_f32_16x16x32_bf16 v[32:35], v[232:235], v[178:181], v[32:35]
	v_mfma_f32_16x16x32_bf16 v[24:27], v[240:243], v[178:181], v[24:27]
	v_mfma_f32_16x16x32_bf16 v[16:19], v[232:235], v[186:189], v[16:19]
	v_mfma_f32_16x16x32_bf16 v[8:11], v[240:243], v[186:189], v[8:11]
	v_mfma_f32_16x16x32_bf16 v[4:7], v[232:235], v[194:197], v[4:7]
	v_mfma_f32_16x16x32_bf16 v[0:3], v[240:243], v[194:197], v[0:3]
	s_add_i32 s30, 0, 0x18000
	v_add_u32_e32 v150, s30, v171
	s_barrier
	ds_read_b128 v[128:131], v150
	ds_read_b128 v[132:135], v150 offset:1024
	ds_read_b128 v[136:139], v150 offset:2048
	ds_read_b128 v[150:153], v150 offset:3072
	s_add_u32 s20, s20, s64
	s_addc_u32 s21, s21, s65
	s_mov_b32 m0, s17
	v_lshl_add_u64 v[198:199], s[20:21], 0, v[140:141]
	ds_read_b128 v[154:157], v173 offset:32768
	ds_read_b128 v[166:169], v173 offset:33792
	ds_read_b128 v[174:177], v173 offset:34816
	ds_read_b128 v[178:181], v173 offset:35840
	ds_read_b128 v[182:185], v173 offset:36864
	ds_read_b128 v[186:189], v173 offset:37888
	ds_read_b128 v[190:193], v173 offset:38912
	ds_read_b128 v[194:197], v173 offset:39936
	global_load_lds_dwordx4 v[198:199], off
	v_lshl_add_u64 v[198:199], s[20:21], 0, v[142:143]
	s_mov_b32 m0, s27
	s_nop 0
	global_load_lds_dwordx4 v[198:199], off
	s_waitcnt lgkmcnt(8)
	s_barrier
	s_waitcnt lgkmcnt(0)
	s_waitcnt lgkmcnt(0)
	v_mfma_f32_16x16x32_bf16 v[124:127], v[128:131], v[154:157], v[124:127]
	v_mfma_f32_16x16x32_bf16 v[120:123], v[136:139], v[154:157], v[120:123]
	v_mfma_f32_16x16x32_bf16 v[112:115], v[128:131], v[174:177], v[112:115]
	v_mfma_f32_16x16x32_bf16 v[108:111], v[136:139], v[174:177], v[108:111]
	v_mfma_f32_16x16x32_bf16 v[100:103], v[128:131], v[182:185], v[100:103]
	v_mfma_f32_16x16x32_bf16 v[92:95], v[136:139], v[182:185], v[92:95]
	v_mfma_f32_16x16x32_bf16 v[84:87], v[128:131], v[190:193], v[84:87]
	v_mfma_f32_16x16x32_bf16 v[76:79], v[136:139], v[190:193], v[76:79]
	v_mfma_f32_16x16x32_bf16 v[124:127], v[132:135], v[166:169], v[124:127]
	v_mfma_f32_16x16x32_bf16 v[120:123], v[150:153], v[166:169], v[120:123]
	v_mfma_f32_16x16x32_bf16 v[112:115], v[132:135], v[178:181], v[112:115]
	v_mfma_f32_16x16x32_bf16 v[108:111], v[150:153], v[178:181], v[108:111]
	v_mfma_f32_16x16x32_bf16 v[100:103], v[132:135], v[186:189], v[100:103]
	v_mfma_f32_16x16x32_bf16 v[92:95], v[150:153], v[186:189], v[92:95]
	v_mfma_f32_16x16x32_bf16 v[84:87], v[132:135], v[194:197], v[84:87]
	v_mfma_f32_16x16x32_bf16 v[76:79], v[150:153], v[194:197], v[76:79]
	s_barrier
	s_add_i32 s20, 0, 0x1c000
	s_add_i32 s21, s30, s23
	v_add_u32_e32 v240, s20, v171
	v_lshl_add_u64 v[158:159], v[158:159], 0, s[96:97]
	s_mov_b32 m0, s21
	ds_read_b128 v[198:201], v240
	ds_read_b128 v[232:235], v240 offset:1024
	ds_read_b128 v[236:239], v240 offset:2048
	ds_read_b128 v[240:243], v240 offset:3072
	global_load_lds_dwordx4 v[158:159], off
	v_lshl_add_u64 v[158:159], v[202:203], 0, s[96:97]
	s_add_i32 m0, s21, 0x2000
	s_nop 0
	global_load_lds_dwordx4 v[158:159], off
	s_barrier
	s_waitcnt lgkmcnt(0)
	s_waitcnt lgkmcnt(0)
	v_mfma_f32_16x16x32_bf16 v[116:119], v[198:201], v[154:157], v[116:119]
	v_mfma_f32_16x16x32_bf16 v[104:107], v[236:239], v[154:157], v[104:107]
	v_mfma_f32_16x16x32_bf16 v[96:99], v[198:201], v[174:177], v[96:99]
	v_mfma_f32_16x16x32_bf16 v[88:91], v[236:239], v[174:177], v[88:91]
	v_mfma_f32_16x16x32_bf16 v[80:83], v[198:201], v[182:185], v[80:83]
	v_mfma_f32_16x16x32_bf16 v[72:75], v[236:239], v[182:185], v[72:75]
	v_mfma_f32_16x16x32_bf16 v[68:71], v[198:201], v[190:193], v[68:71]
	v_mfma_f32_16x16x32_bf16 v[64:67], v[236:239], v[190:193], v[64:67]
	v_mfma_f32_16x16x32_bf16 v[116:119], v[232:235], v[166:169], v[116:119]
	v_mfma_f32_16x16x32_bf16 v[104:107], v[240:243], v[166:169], v[104:107]
	v_mfma_f32_16x16x32_bf16 v[96:99], v[232:235], v[178:181], v[96:99]
	v_mfma_f32_16x16x32_bf16 v[88:91], v[240:243], v[178:181], v[88:91]
	v_mfma_f32_16x16x32_bf16 v[80:83], v[232:235], v[186:189], v[80:83]
	v_mfma_f32_16x16x32_bf16 v[72:75], v[240:243], v[186:189], v[72:75]
	v_mfma_f32_16x16x32_bf16 v[68:71], v[232:235], v[194:197], v[68:71]
	v_mfma_f32_16x16x32_bf16 v[64:67], v[240:243], v[194:197], v[64:67]
	s_mov_b32 m0, s28
	v_lshl_add_u64 v[158:159], v[206:207], 0, s[96:97]
	s_barrier
	ds_read_b128 v[154:157], v173 offset:49152
	ds_read_b128 v[166:169], v173 offset:50176
	ds_read_b128 v[174:177], v173 offset:51200
	ds_read_b128 v[178:181], v173 offset:52224
	ds_read_b128 v[182:185], v173 offset:53248
	ds_read_b128 v[186:189], v173 offset:54272
	ds_read_b128 v[190:193], v173 offset:55296
	ds_read_b128 v[194:197], v173 offset:56320
	global_load_lds_dwordx4 v[158:159], off
	v_lshl_add_u64 v[158:159], v[210:211], 0, s[96:97]
	s_mov_b32 m0, s29
	s_nop 0
	global_load_lds_dwordx4 v[158:159], off
	s_barrier
	s_waitcnt lgkmcnt(0)
	s_waitcnt lgkmcnt(0)
	v_mfma_f32_16x16x32_bf16 v[60:63], v[128:131], v[154:157], v[60:63]
	v_mfma_f32_16x16x32_bf16 v[56:59], v[136:139], v[154:157], v[56:59]
	v_mfma_f32_16x16x32_bf16 v[52:55], v[128:131], v[174:177], v[52:55]
	v_mfma_f32_16x16x32_bf16 v[44:47], v[136:139], v[174:177], v[44:47]
	v_mfma_f32_16x16x32_bf16 v[36:39], v[128:131], v[182:185], v[36:39]
	v_mfma_f32_16x16x32_bf16 v[28:31], v[136:139], v[182:185], v[28:31]
	v_mfma_f32_16x16x32_bf16 v[20:23], v[128:131], v[190:193], v[20:23]
	v_mfma_f32_16x16x32_bf16 v[12:15], v[136:139], v[190:193], v[12:15]
	v_mfma_f32_16x16x32_bf16 v[60:63], v[132:135], v[166:169], v[60:63]
	v_mfma_f32_16x16x32_bf16 v[56:59], v[150:153], v[166:169], v[56:59]
	v_mfma_f32_16x16x32_bf16 v[52:55], v[132:135], v[178:181], v[52:55]
	v_mfma_f32_16x16x32_bf16 v[44:47], v[150:153], v[178:181], v[44:47]
	v_mfma_f32_16x16x32_bf16 v[36:39], v[132:135], v[186:189], v[36:39]
	v_mfma_f32_16x16x32_bf16 v[28:31], v[150:153], v[186:189], v[28:31]
	v_mfma_f32_16x16x32_bf16 v[20:23], v[132:135], v[194:197], v[20:23]
	v_mfma_f32_16x16x32_bf16 v[12:15], v[150:153], v[194:197], v[12:15]
	s_barrier
	s_add_i32 s20, s20, s23
	v_lshl_add_u64 v[128:129], v[244:245], 0, s[96:97]
	s_mov_b32 m0, s20
	s_nop 0
	global_load_lds_dwordx4 v[128:129], off
	v_lshl_add_u64 v[128:129], v[246:247], 0, s[96:97]
	s_add_i32 m0, s20, 0x2000
	s_nop 0
	global_load_lds_dwordx4 v[128:129], off
	s_waitcnt vmcnt(6)
	s_barrier
	v_mfma_f32_16x16x32_bf16 v[48:51], v[198:201], v[154:157], v[48:51]
	v_mfma_f32_16x16x32_bf16 v[40:43], v[236:239], v[154:157], v[40:43]
	v_mfma_f32_16x16x32_bf16 v[32:35], v[198:201], v[174:177], v[32:35]
	v_mfma_f32_16x16x32_bf16 v[24:27], v[236:239], v[174:177], v[24:27]
	v_mfma_f32_16x16x32_bf16 v[16:19], v[198:201], v[182:185], v[16:19]
	v_mfma_f32_16x16x32_bf16 v[8:11], v[236:239], v[182:185], v[8:11]
	v_mfma_f32_16x16x32_bf16 v[4:7], v[198:201], v[190:193], v[4:7]
	v_mfma_f32_16x16x32_bf16 v[0:3], v[236:239], v[190:193], v[0:3]
	v_mfma_f32_16x16x32_bf16 v[48:51], v[232:235], v[166:169], v[48:51]
	v_mfma_f32_16x16x32_bf16 v[40:43], v[240:243], v[166:169], v[40:43]
	v_mfma_f32_16x16x32_bf16 v[32:35], v[232:235], v[178:181], v[32:35]
	v_mfma_f32_16x16x32_bf16 v[24:27], v[240:243], v[178:181], v[24:27]
	v_mfma_f32_16x16x32_bf16 v[16:19], v[232:235], v[186:189], v[16:19]
	v_mfma_f32_16x16x32_bf16 v[8:11], v[240:243], v[186:189], v[8:11]
	v_mfma_f32_16x16x32_bf16 v[4:7], v[232:235], v[194:197], v[4:7]
	v_mfma_f32_16x16x32_bf16 v[0:3], v[240:243], v[194:197], v[0:3]
	s_add_u32 s3, s3, 0x100
	s_addc_u32 s34, s34, 0
	s_add_u32 s8, s8, 0x100
	s_addc_u32 s9, s9, 0
	s_cmp_ge_i32 s35, s41
	s_mov_b32 s20, s35
	s_barrier
	s_cbranch_scc0 .LBB0_277
	v_readlane_b32 s8, v254, 5
	v_mov_b32 v128, s8
	v_readlane_b32 s9, v254, 6
	v_readfirstlane_b32 s89, v128
	v_mov_b32 v128, s9
	s_add_u32 s3, s89, 0x14400000
	v_readfirstlane_b32 s90, v128
	s_addc_u32 s88, s90, 0
	s_add_u32 s8, s89, 0xc400000
	s_addc_u32 s9, s90, 0
	s_mov_b64 s[30:31], -1
	s_mov_b64 s[20:21], 0
	s_cmp_lt_i32 s2, 5
	s_mov_b64 s[78:79], 0
	s_mov_b64 s[82:83], 0
	s_cbranch_scc1 .LBB0_282
	s_mov_b64 s[82:83], -1
	s_mov_b64 s[30:31], 0
	s_cmp_gt_i32 s2, 5
	s_cbranch_scc0 .LBB0_282
	s_cmp_gt_i32 s2, 6
	s_cbranch_scc0 .LBB0_303
	s_cmp_eq_u32 s2, 7
	s_cselect_b64 s[82:83], -1, 0
